# v55 + P11 GEMM loop: in each load segment the global->LDS stage loads are issued before the ds_read fragment reads (loads start earlier relative to their deadline)
# speedup vs baseline: 1.0102x; 1.0102x over previous
.LBB0_975:
	s_add_u32 s40, s38, 0xfff80080
	s_addc_u32 s41, s39, -1
	s_cmp_eq_u32 s59, 28
	s_cselect_b32 s43, s1, s41
	s_cselect_b32 s42, s3, s40
	s_cselect_b32 s41, s29, s58
	s_cselect_b32 s40, s31, s57
	v_lshl_add_u64 v[224:225], s[38:39], 0, v[156:157]
	s_add_i32 m0, s33, 0xc000
	s_nop 0
	global_load_lds_dwordx4 v[224:225], off
	v_lshl_add_u64 v[224:225], s[38:39], 0, v[158:159]
	s_add_i32 m0, s33, 0xe000
	s_nop 0
	global_load_lds_dwordx4 v[224:225], off
	ds_read_b128 v[116:119], v185
	ds_read_b128 v[120:123], v185 offset:1024
	ds_read_b128 v[124:127], v185 offset:2048
	ds_read_b128 v[132:135], v185 offset:3072
	ds_read_b128 v[166:169], v186
	ds_read_b128 v[170:173], v186 offset:1024
	ds_read_b128 v[174:177], v186 offset:2048
	ds_read_b128 v[178:181], v186 offset:3072
	ds_read_b128 v[192:195], v187
	ds_read_b128 v[196:199], v187 offset:1024
	ds_read_b128 v[200:203], v187 offset:2048
	ds_read_b128 v[204:207], v187 offset:3072
	ds_read_b128 v[208:211], v187 offset:4096
	ds_read_b128 v[212:215], v187 offset:5120
	ds_read_b128 v[216:219], v187 offset:6144
	ds_read_b128 v[220:223], v187 offset:7168
	s_waitcnt vmcnt(8)
	s_waitcnt lgkmcnt(0)
	s_barrier
	s_setprio 1
	s_waitcnt lgkmcnt(0)
	v_mfma_f32_16x16x32_bf16 v[136:139], v[116:119], v[192:195], v[136:139]
	v_mfma_f32_16x16x32_bf16 v[56:59], v[124:127], v[192:195], v[56:59]
	v_mfma_f32_16x16x32_bf16 v[112:115], v[116:119], v[200:203], v[112:115]
	v_mfma_f32_16x16x32_bf16 v[48:51], v[124:127], v[200:203], v[48:51]
	v_mfma_f32_16x16x32_bf16 v[104:107], v[116:119], v[208:211], v[104:107]
	v_mfma_f32_16x16x32_bf16 v[40:43], v[124:127], v[208:211], v[40:43]
	v_mfma_f32_16x16x32_bf16 v[100:103], v[116:119], v[216:219], v[100:103]
	v_mfma_f32_16x16x32_bf16 v[36:39], v[124:127], v[216:219], v[36:39]
	v_mfma_f32_16x16x32_bf16 v[136:139], v[120:123], v[196:199], v[136:139]
	v_mfma_f32_16x16x32_bf16 v[56:59], v[132:135], v[196:199], v[56:59]
	v_mfma_f32_16x16x32_bf16 v[112:115], v[120:123], v[204:207], v[112:115]
	v_mfma_f32_16x16x32_bf16 v[48:51], v[132:135], v[204:207], v[48:51]
	v_mfma_f32_16x16x32_bf16 v[104:107], v[120:123], v[212:215], v[104:107]
	v_mfma_f32_16x16x32_bf16 v[40:43], v[132:135], v[212:215], v[40:43]
	v_mfma_f32_16x16x32_bf16 v[100:103], v[120:123], v[220:223], v[100:103]
	v_mfma_f32_16x16x32_bf16 v[36:39], v[132:135], v[220:223], v[36:39]
	v_mfma_f32_16x16x32_bf16 v[140:143], v[166:169], v[192:195], v[140:143]
	v_mfma_f32_16x16x32_bf16 v[60:63], v[174:177], v[192:195], v[60:63]
	v_mfma_f32_16x16x32_bf16 v[128:131], v[166:169], v[200:203], v[128:131]
	v_mfma_f32_16x16x32_bf16 v[52:55], v[174:177], v[200:203], v[52:55]
	v_mfma_f32_16x16x32_bf16 v[108:111], v[166:169], v[208:211], v[108:111]
	v_mfma_f32_16x16x32_bf16 v[44:47], v[174:177], v[208:211], v[44:47]
	v_mfma_f32_16x16x32_bf16 v[96:99], v[166:169], v[216:219], v[96:99]
	v_mfma_f32_16x16x32_bf16 v[32:35], v[174:177], v[216:219], v[32:35]
	v_mfma_f32_16x16x32_bf16 v[140:143], v[170:173], v[196:199], v[140:143]
	v_mfma_f32_16x16x32_bf16 v[60:63], v[178:181], v[196:199], v[60:63]
	v_mfma_f32_16x16x32_bf16 v[128:131], v[170:173], v[204:207], v[128:131]
	v_mfma_f32_16x16x32_bf16 v[52:55], v[178:181], v[204:207], v[52:55]
	v_mfma_f32_16x16x32_bf16 v[108:111], v[170:173], v[212:215], v[108:111]
	v_mfma_f32_16x16x32_bf16 v[44:47], v[178:181], v[212:215], v[44:47]
	v_mfma_f32_16x16x32_bf16 v[96:99], v[170:173], v[220:223], v[96:99]
	v_mfma_f32_16x16x32_bf16 v[32:35], v[178:181], v[220:223], v[32:35]
	s_setprio 0
	s_barrier
	s_add_i32 s60, s53, s93
	v_lshl_add_u64 v[224:225], s[40:41], 0, v[146:147]
	s_mov_b32 m0, s60
	s_nop 0
	global_load_lds_dwordx4 v[224:225], off
	s_add_i32 m0, s60, 0x2000
	s_add_u32 s60, s40, 0x80000
	v_lshl_add_u64 v[226:227], s[40:41], 0, v[150:151]
	s_addc_u32 s61, s41, 0
	s_add_i32 s62, s54, s93
	global_load_lds_dwordx4 v[226:227], off
	v_lshl_add_u64 v[228:229], s[60:61], 0, v[146:147]
	s_mov_b32 m0, s62
	v_lshl_add_u64 v[230:231], s[42:43], 0, v[148:149]
	global_load_lds_dwordx4 v[228:229], off
	v_lshl_add_u64 v[228:229], s[60:61], 0, v[150:151]
	s_add_i32 m0, s62, 0x2000
	s_nop 0
	global_load_lds_dwordx4 v[228:229], off
	v_lshl_add_u64 v[228:229], s[42:43], 0, v[144:145]
	s_mov_b32 m0, s33
	s_nop 0
	global_load_lds_dwordx4 v[228:229], off
	s_mov_b32 m0, s44
	s_nop 0
	global_load_lds_dwordx4 v[230:231], off
	ds_read_b128 v[192:195], v187 offset:16384
	ds_read_b128 v[196:199], v187 offset:17408
	ds_read_b128 v[200:203], v187 offset:18432
	ds_read_b128 v[204:207], v187 offset:19456
	ds_read_b128 v[208:211], v187 offset:20480
	ds_read_b128 v[212:215], v187 offset:21504
	ds_read_b128 v[216:219], v187 offset:22528
	ds_read_b128 v[220:223], v187 offset:23552
	s_waitcnt vmcnt(8)
	s_waitcnt lgkmcnt(0)
	s_barrier
	s_setprio 1
	s_waitcnt lgkmcnt(0)
	v_mfma_f32_16x16x32_bf16 v[88:91], v[116:119], v[192:195], v[88:91]
	v_mfma_f32_16x16x32_bf16 v[24:27], v[124:127], v[192:195], v[24:27]
	v_mfma_f32_16x16x32_bf16 v[80:83], v[116:119], v[200:203], v[80:83]
	v_mfma_f32_16x16x32_bf16 v[16:19], v[124:127], v[200:203], v[16:19]
	v_mfma_f32_16x16x32_bf16 v[72:75], v[116:119], v[208:211], v[72:75]
	v_mfma_f32_16x16x32_bf16 v[8:11], v[124:127], v[208:211], v[8:11]
	v_mfma_f32_16x16x32_bf16 v[68:71], v[116:119], v[216:219], v[68:71]
	v_mfma_f32_16x16x32_bf16 v[4:7], v[124:127], v[216:219], v[4:7]
	v_mfma_f32_16x16x32_bf16 v[88:91], v[120:123], v[196:199], v[88:91]
	v_mfma_f32_16x16x32_bf16 v[24:27], v[132:135], v[196:199], v[24:27]
	v_mfma_f32_16x16x32_bf16 v[80:83], v[120:123], v[204:207], v[80:83]
	v_mfma_f32_16x16x32_bf16 v[16:19], v[132:135], v[204:207], v[16:19]
	v_mfma_f32_16x16x32_bf16 v[72:75], v[120:123], v[212:215], v[72:75]
	v_mfma_f32_16x16x32_bf16 v[8:11], v[132:135], v[212:215], v[8:11]
	v_mfma_f32_16x16x32_bf16 v[68:71], v[120:123], v[220:223], v[68:71]
	v_mfma_f32_16x16x32_bf16 v[4:7], v[132:135], v[220:223], v[4:7]
	v_mfma_f32_16x16x32_bf16 v[92:95], v[166:169], v[192:195], v[92:95]
	v_mfma_f32_16x16x32_bf16 v[28:31], v[174:177], v[192:195], v[28:31]
	v_mfma_f32_16x16x32_bf16 v[84:87], v[166:169], v[200:203], v[84:87]
	v_mfma_f32_16x16x32_bf16 v[20:23], v[174:177], v[200:203], v[20:23]
	v_mfma_f32_16x16x32_bf16 v[76:79], v[166:169], v[208:211], v[76:79]
	v_mfma_f32_16x16x32_bf16 v[12:15], v[174:177], v[208:211], v[12:15]
	v_mfma_f32_16x16x32_bf16 v[64:67], v[166:169], v[216:219], v[64:67]
	v_mfma_f32_16x16x32_bf16 v[0:3], v[174:177], v[216:219], v[0:3]
	v_mfma_f32_16x16x32_bf16 v[92:95], v[170:173], v[196:199], v[92:95]
	v_mfma_f32_16x16x32_bf16 v[28:31], v[178:181], v[196:199], v[28:31]
	v_mfma_f32_16x16x32_bf16 v[84:87], v[170:173], v[204:207], v[84:87]
	v_mfma_f32_16x16x32_bf16 v[20:23], v[178:181], v[204:207], v[20:23]
	v_mfma_f32_16x16x32_bf16 v[76:79], v[170:173], v[212:215], v[76:79]
	v_mfma_f32_16x16x32_bf16 v[12:15], v[178:181], v[212:215], v[12:15]
	v_mfma_f32_16x16x32_bf16 v[64:67], v[170:173], v[220:223], v[64:67]
	v_mfma_f32_16x16x32_bf16 v[0:3], v[178:181], v[220:223], v[0:3]
	s_setprio 0
	s_barrier
	s_add_i32 s60, 0, 0x18000
	s_add_i32 s61, 0, 0x1c000
	v_add_u32_e32 v132, s60, v183
	v_add_u32_e32 v178, s61, v183
	s_add_u32 s42, s42, 0x80000
	s_addc_u32 s43, s43, 0
	s_mov_b32 m0, s45
	v_lshl_add_u64 v[232:233], s[42:43], 0, v[144:145]
	global_load_lds_dwordx4 v[232:233], off
	v_lshl_add_u64 v[232:233], s[42:43], 0, v[148:149]
	s_mov_b32 m0, s46
	s_nop 0
	global_load_lds_dwordx4 v[232:233], off
	ds_read_b128 v[116:119], v132
	ds_read_b128 v[120:123], v132 offset:1024
	ds_read_b128 v[124:127], v132 offset:2048
	ds_read_b128 v[132:135], v132 offset:3072
	ds_read_b128 v[166:169], v178
	ds_read_b128 v[170:173], v178 offset:1024
	ds_read_b128 v[174:177], v178 offset:2048
	ds_read_b128 v[178:181], v178 offset:3072
	ds_read_b128 v[192:195], v187 offset:32768
	ds_read_b128 v[196:199], v187 offset:33792
	ds_read_b128 v[200:203], v187 offset:34816
	ds_read_b128 v[204:207], v187 offset:35840
	ds_read_b128 v[208:211], v187 offset:36864
	ds_read_b128 v[212:215], v187 offset:37888
	ds_read_b128 v[216:219], v187 offset:38912
	ds_read_b128 v[220:223], v187 offset:39936
	s_waitcnt vmcnt(8)
	s_waitcnt lgkmcnt(0)
	s_barrier
	s_setprio 1
	s_waitcnt lgkmcnt(0)
	v_mfma_f32_16x16x32_bf16 v[136:139], v[116:119], v[192:195], v[136:139]
	v_mfma_f32_16x16x32_bf16 v[56:59], v[124:127], v[192:195], v[56:59]
	v_mfma_f32_16x16x32_bf16 v[112:115], v[116:119], v[200:203], v[112:115]
	v_mfma_f32_16x16x32_bf16 v[48:51], v[124:127], v[200:203], v[48:51]
	v_mfma_f32_16x16x32_bf16 v[104:107], v[116:119], v[208:211], v[104:107]
	v_mfma_f32_16x16x32_bf16 v[40:43], v[124:127], v[208:211], v[40:43]
	v_mfma_f32_16x16x32_bf16 v[100:103], v[116:119], v[216:219], v[100:103]
	v_mfma_f32_16x16x32_bf16 v[36:39], v[124:127], v[216:219], v[36:39]
	v_mfma_f32_16x16x32_bf16 v[136:139], v[120:123], v[196:199], v[136:139]
	v_mfma_f32_16x16x32_bf16 v[56:59], v[132:135], v[196:199], v[56:59]
	v_mfma_f32_16x16x32_bf16 v[112:115], v[120:123], v[204:207], v[112:115]
	v_mfma_f32_16x16x32_bf16 v[48:51], v[132:135], v[204:207], v[48:51]
	v_mfma_f32_16x16x32_bf16 v[104:107], v[120:123], v[212:215], v[104:107]
	v_mfma_f32_16x16x32_bf16 v[40:43], v[132:135], v[212:215], v[40:43]
	v_mfma_f32_16x16x32_bf16 v[100:103], v[120:123], v[220:223], v[100:103]
	v_mfma_f32_16x16x32_bf16 v[36:39], v[132:135], v[220:223], v[36:39]
	v_mfma_f32_16x16x32_bf16 v[140:143], v[166:169], v[192:195], v[140:143]
	v_mfma_f32_16x16x32_bf16 v[60:63], v[174:177], v[192:195], v[60:63]
	v_mfma_f32_16x16x32_bf16 v[128:131], v[166:169], v[200:203], v[128:131]
	v_mfma_f32_16x16x32_bf16 v[52:55], v[174:177], v[200:203], v[52:55]
	v_mfma_f32_16x16x32_bf16 v[108:111], v[166:169], v[208:211], v[108:111]
	v_mfma_f32_16x16x32_bf16 v[44:47], v[174:177], v[208:211], v[44:47]
	v_mfma_f32_16x16x32_bf16 v[96:99], v[166:169], v[216:219], v[96:99]
	v_mfma_f32_16x16x32_bf16 v[32:35], v[174:177], v[216:219], v[32:35]
	v_mfma_f32_16x16x32_bf16 v[140:143], v[170:173], v[196:199], v[140:143]
	v_mfma_f32_16x16x32_bf16 v[60:63], v[178:181], v[196:199], v[60:63]
	v_mfma_f32_16x16x32_bf16 v[128:131], v[170:173], v[204:207], v[128:131]
	v_mfma_f32_16x16x32_bf16 v[52:55], v[178:181], v[204:207], v[52:55]
	v_mfma_f32_16x16x32_bf16 v[108:111], v[170:173], v[212:215], v[108:111]
	v_mfma_f32_16x16x32_bf16 v[44:47], v[178:181], v[212:215], v[44:47]
	v_mfma_f32_16x16x32_bf16 v[96:99], v[170:173], v[220:223], v[96:99]
	v_mfma_f32_16x16x32_bf16 v[32:35], v[178:181], v[220:223], v[32:35]
	s_setprio 0
	s_barrier
	s_add_i32 s42, s60, s93
	v_lshl_add_u64 v[224:225], v[224:225], 0, s[20:21]
	s_mov_b32 m0, s42
	s_nop 0
	global_load_lds_dwordx4 v[224:225], off
	s_add_i32 m0, s42, 0x2000
	s_add_u32 s40, s40, 0x80080
	v_lshl_add_u64 v[224:225], v[226:227], 0, s[20:21]
	s_addc_u32 s41, s41, 0
	s_add_i32 s42, s61, s93
	global_load_lds_dwordx4 v[224:225], off
	v_lshl_add_u64 v[224:225], s[40:41], 0, v[146:147]
	s_mov_b32 m0, s42
	s_nop 0
	global_load_lds_dwordx4 v[224:225], off
	v_lshl_add_u64 v[224:225], s[40:41], 0, v[150:151]
	s_add_i32 m0, s42, 0x2000
	s_nop 0
	global_load_lds_dwordx4 v[224:225], off
	v_lshl_add_u64 v[224:225], v[228:229], 0, s[20:21]
	s_mov_b32 m0, s48
	s_nop 0
	global_load_lds_dwordx4 v[224:225], off
	v_lshl_add_u64 v[224:225], v[230:231], 0, s[20:21]
	s_mov_b32 m0, s49
	s_nop 0
	global_load_lds_dwordx4 v[224:225], off
	ds_read_b128 v[192:195], v187 offset:49152
	ds_read_b128 v[196:199], v187 offset:50176
	ds_read_b128 v[200:203], v187 offset:51200
	ds_read_b128 v[204:207], v187 offset:52224
	ds_read_b128 v[208:211], v187 offset:53248
	ds_read_b128 v[212:215], v187 offset:54272
	ds_read_b128 v[216:219], v187 offset:55296
	ds_read_b128 v[220:223], v187 offset:56320
	s_waitcnt vmcnt(8)
	s_waitcnt lgkmcnt(0)
	s_barrier
	s_setprio 1
	s_waitcnt lgkmcnt(0)
	v_mfma_f32_16x16x32_bf16 v[88:91], v[116:119], v[192:195], v[88:91]
	v_mfma_f32_16x16x32_bf16 v[24:27], v[124:127], v[192:195], v[24:27]
	v_mfma_f32_16x16x32_bf16 v[80:83], v[116:119], v[200:203], v[80:83]
	v_mfma_f32_16x16x32_bf16 v[16:19], v[124:127], v[200:203], v[16:19]
	v_mfma_f32_16x16x32_bf16 v[72:75], v[116:119], v[208:211], v[72:75]
	v_mfma_f32_16x16x32_bf16 v[8:11], v[124:127], v[208:211], v[8:11]
	v_mfma_f32_16x16x32_bf16 v[68:71], v[116:119], v[216:219], v[68:71]
	v_mfma_f32_16x16x32_bf16 v[4:7], v[124:127], v[216:219], v[4:7]
	v_mfma_f32_16x16x32_bf16 v[88:91], v[120:123], v[196:199], v[88:91]
	v_mfma_f32_16x16x32_bf16 v[24:27], v[132:135], v[196:199], v[24:27]
	v_mfma_f32_16x16x32_bf16 v[80:83], v[120:123], v[204:207], v[80:83]
	v_mfma_f32_16x16x32_bf16 v[16:19], v[132:135], v[204:207], v[16:19]
	v_mfma_f32_16x16x32_bf16 v[72:75], v[120:123], v[212:215], v[72:75]
	v_mfma_f32_16x16x32_bf16 v[8:11], v[132:135], v[212:215], v[8:11]
	v_mfma_f32_16x16x32_bf16 v[68:71], v[120:123], v[220:223], v[68:71]
	v_mfma_f32_16x16x32_bf16 v[4:7], v[132:135], v[220:223], v[4:7]
	v_mfma_f32_16x16x32_bf16 v[92:95], v[166:169], v[192:195], v[92:95]
	v_mfma_f32_16x16x32_bf16 v[28:31], v[174:177], v[192:195], v[28:31]
	v_mfma_f32_16x16x32_bf16 v[84:87], v[166:169], v[200:203], v[84:87]
	v_mfma_f32_16x16x32_bf16 v[20:23], v[174:177], v[200:203], v[20:23]
	v_mfma_f32_16x16x32_bf16 v[76:79], v[166:169], v[208:211], v[76:79]
	v_mfma_f32_16x16x32_bf16 v[12:15], v[174:177], v[208:211], v[12:15]
	v_mfma_f32_16x16x32_bf16 v[64:67], v[166:169], v[216:219], v[64:67]
	v_mfma_f32_16x16x32_bf16 v[0:3], v[174:177], v[216:219], v[0:3]
	v_mfma_f32_16x16x32_bf16 v[92:95], v[170:173], v[196:199], v[92:95]
	v_mfma_f32_16x16x32_bf16 v[28:31], v[178:181], v[196:199], v[28:31]
	v_mfma_f32_16x16x32_bf16 v[84:87], v[170:173], v[204:207], v[84:87]
	v_mfma_f32_16x16x32_bf16 v[20:23], v[178:181], v[204:207], v[20:23]
	v_mfma_f32_16x16x32_bf16 v[76:79], v[170:173], v[212:215], v[76:79]
	v_mfma_f32_16x16x32_bf16 v[12:15], v[178:181], v[212:215], v[12:15]
	v_mfma_f32_16x16x32_bf16 v[64:67], v[170:173], v[220:223], v[64:67]
	v_mfma_f32_16x16x32_bf16 v[0:3], v[178:181], v[220:223], v[0:3]
	s_setprio 0
	s_barrier
	s_add_i32 s59, s59, 2
	s_add_u32 s38, s38, 0x100
	s_addc_u32 s39, s39, 0
	s_add_u32 s57, s57, 0x100
	s_addc_u32 s58, s58, 0
	s_cmp_gt_u32 s59, 29
	s_cbranch_scc0 .LBB0_975
	s_and_b64 vcc, exec, s[22:23]
	s_cbranch_vccz .LBB0_978
	s_barrier
